# nt cache policy on the once-read f32 weight loads of the weight item loop (plus cache_convert fast paths); stores keep the default policy
# speedup vs baseline: 1.0081x; 1.0081x over previous
; #define LAS __attribute__((address_space(3)))
; __device__ __forceinline__ unsigned cvt_pk_bf16(float lo, float hi) { unsigned r; asm("v_cvt_pk_bf16_f32 %0, %1, %2" : "=v"(r) : "v"(lo), "v"(hi)); return r; }
; __device__ __forceinline__ void transpose_item(const float* W, int K, int N, const float* gain, bf16_t* WT, int dst_row0, LAS float* scr, int kb, int n0, int lane) {
;     const int k0 = 64 * kb, n4 = (lane & 7) * 4, kr = lane >> 3;
;     f32x4 v[8]; float g[8];
; #pragma unroll
;     for (int i = 0; i < 8; ++i) { v[i] = *(const f32x4*)(W + (size_t)(k0 + kr + 8 * i) * N + n0 + n4); g[i] = gain ? gain[k0 + kr + 8 * i] : 1.0f; }
; #pragma unroll
;     for (int i = 0; i < 8; ++i) { LAS float* d = scr + (kr + 8 * i) * 33 + n4; d[0] = v[i][0] * g[i]; d[1] = v[i][1] * g[i]; d[2] = v[i][2] * g[i]; d[3] = v[i][3] * g[i]; }
;     asm volatile("s_waitcnt lgkmcnt(0)" ::: "memory");
;     const int c = lane & 7;
; #pragma unroll
;     for (int j = 0; j < 4; ++j) { const int n = (lane >> 3) + 8 * j; const LAS float* s = scr + (8 * c) * 33 + n;
;         u32x4 o; o.x = cvt_pk_bf16(s[0 * 33], s[1 * 33]); o.y = cvt_pk_bf16(s[2 * 33], s[3 * 33]); o.z = cvt_pk_bf16(s[4 * 33], s[5 * 33]); o.w = cvt_pk_bf16(s[6 * 33], s[7 * 33]);
;         *(u32x4*)(WT + (size_t)(dst_row0 + n) * K + k0 + 8 * c) = o; }
;     asm volatile("s_waitcnt lgkmcnt(0)" ::: "memory");
; }
; __device__ __forceinline__ void weight_item(const Params& P, unsigned char* ws, LAS float* scr, int l, int r, int lane) {
;     ...
;             else if (q == 2) transpose_item(P.in[26] + oS, D, D, nullptr, (bf16_t*)(ws + WS_WXO) + oS, n0, scr, kb, n0, lane);
.LBB0_58:
	s_andn2_b64 vcc, exec, s[2:3]
	s_cbranch_vccnz .LBB0_60
	s_load_dwordx16 s[64:79], s[0:1], 0xc0
	s_lshl_b64 s[2:3], s[22:23], 2
	v_mov_b32_e32 v43, v37
	v_lshlrev_b32_e32 v4, 12, v1
	v_lshl_or_b32 v36, s56, 18, v4
	s_waitcnt lgkmcnt(0)
	s_add_u32 s16, s68, s2
	s_addc_u32 s24, s69, s3
	s_lshl_b64 s[2:3], s[22:23], 1
	s_add_u32 s25, s34, s2
	s_addc_u32 s57, s35, s3
	s_lshl_b32 s2, s19, 2
	s_add_u32 s2, s16, s2
	s_addc_u32 s3, s24, 0
	v_lshl_add_u64 v[2:3], s[2:3], 0, v[42:43]
	v_lshl_add_u64 v[30:31], v[2:3], 0, v[36:37]
	s_mov_b32 s2, 0x8000
	v_add_co_u32_e32 v6, vcc, s2, v30
	s_mov_b32 s2, 0x10000
	s_nop 0
	v_addc_co_u32_e32 v7, vcc, 0, v31, vcc
	v_add_co_u32_e32 v10, vcc, s2, v30
	s_mov_b32 s2, 0x18000
	s_nop 0
	v_addc_co_u32_e32 v11, vcc, 0, v31, vcc
	v_add_co_u32_e32 v14, vcc, s2, v30
	s_mov_b32 s2, 0x20000
	s_nop 0
	v_addc_co_u32_e32 v15, vcc, 0, v31, vcc
	v_add_co_u32_e32 v18, vcc, s2, v30
	s_mov_b32 s2, 0x28000
	s_nop 0
	v_addc_co_u32_e32 v19, vcc, 0, v31, vcc
	v_add_co_u32_e32 v22, vcc, s2, v30
	global_load_dwordx4 v[2:5], v[30:31], off nt
	s_nop 0
	global_load_dwordx4 v[6:9], v[6:7], off nt
	v_addc_co_u32_e32 v23, vcc, 0, v31, vcc
	global_load_dwordx4 v[10:13], v[10:11], off nt
	s_nop 0
	global_load_dwordx4 v[14:17], v[14:15], off nt
	s_nop 0
	global_load_dwordx4 v[18:21], v[18:19], off nt
	s_nop 0
	global_load_dwordx4 v[22:25], v[22:23], off nt
	s_mov_b32 s2, 0x30000
	v_add_co_u32_e32 v26, vcc, s2, v30
	s_mov_b32 s2, 0x38000
	s_nop 0
	v_addc_co_u32_e32 v27, vcc, 0, v31, vcc
	global_load_dwordx4 v[26:29], v[26:27], off nt
	v_add_co_u32_e32 v30, vcc, s2, v30
	v_add_u32_e32 v43, v35, v39
	s_nop 0
	v_addc_co_u32_e32 v31, vcc, 0, v31, vcc
	global_load_dwordx4 v[30:33], v[30:31], off nt
	v_add_u32_e32 v44, 0x420, v43
	v_add_u32_e32 v46, 0x428, v43
	v_add_u32_e32 v48, 0x840, v43
	v_add_u32_e32 v49, 0x848, v43
	v_add_u32_e32 v50, 0xc60, v43
	v_add_u32_e32 v52, 0xc68, v43
	v_add_u32_e32 v54, 0x1080, v43
	v_add_u32_e32 v56, 0x1088, v43
	v_add_u32_e32 v58, 0x14a0, v43
	v_add_u32_e32 v65, 0x14a8, v43
	v_add_u32_e32 v66, 0x18c0, v43
	v_add_u32_e32 v67, 0x18c8, v43
	v_add_u32_e32 v68, 0x1ce0, v43
	v_add_u32_e32 v69, 0x1ce8, v43
	s_lshl_b32 s2, s56, 7
	s_add_u32 s2, s25, s2
	s_addc_u32 s3, s57, 0
	v_lshlrev_b32_e32 v36, 1, v38
	s_waitcnt vmcnt(7)
	ds_write2_b32 v43, v2, v3 offset1:1
	ds_write2_b32 v43, v4, v5 offset0:2 offset1:3
	s_waitcnt vmcnt(6)
	ds_write2_b32 v44, v6, v7 offset1:1
	ds_write2_b32 v46, v8, v9 offset1:1
	s_waitcnt vmcnt(5)
	ds_write2_b32 v48, v10, v11 offset1:1
	ds_write2_b32 v49, v12, v13 offset1:1
	s_waitcnt vmcnt(4)
	ds_write2_b32 v50, v14, v15 offset1:1
	ds_write2_b32 v52, v16, v17 offset1:1
	s_waitcnt vmcnt(3)
	ds_write2_b32 v54, v18, v19 offset1:1
	ds_write2_b32 v56, v20, v21 offset1:1
	s_waitcnt vmcnt(2)
	ds_write2_b32 v58, v22, v23 offset1:1
	ds_write2_b32 v65, v24, v25 offset1:1
	s_waitcnt vmcnt(1)
	ds_write2_b32 v66, v26, v27 offset1:1
	ds_write2_b32 v67, v28, v29 offset1:1
	s_waitcnt vmcnt(0)
	ds_write2_b32 v68, v30, v31 offset1:1
	ds_write2_b32 v69, v32, v33 offset1:1
	s_waitcnt lgkmcnt(0)
	ds_read2_b32 v[6:7], v53 offset0:33 offset1:41
	ds_read2_b32 v[8:9], v53 offset1:8
	ds_read2_b32 v[10:11], v53 offset0:66 offset1:74
	ds_read2_b32 v[12:13], v53 offset0:99 offset1:107
	ds_read2_b32 v[14:15], v53 offset0:132 offset1:140
	ds_read2_b32 v[16:17], v53 offset0:165 offset1:173
	ds_read2_b32 v[18:19], v53 offset0:198 offset1:206
	ds_read2_b32 v[20:21], v53 offset0:231 offset1:239
	s_waitcnt lgkmcnt(6)
	v_cvt_pk_bf16_f32 v2, v8, v6
	v_or_b32_e32 v6, s19, v1
	v_lshl_add_u64 v[22:23], s[2:3], 0, v[36:37]
	v_lshlrev_b32_e32 v36, 11, v6
	v_lshl_add_u64 v[24:25], v[22:23], 0, v[36:37]
	s_waitcnt lgkmcnt(4)
	v_cvt_pk_bf16_f32 v3, v10, v12
	s_waitcnt lgkmcnt(2)
	v_cvt_pk_bf16_f32 v4, v14, v16
	s_waitcnt lgkmcnt(0)
	v_cvt_pk_bf16_f32 v5, v18, v20
	global_store_dwordx4 v[24:25], v[2:5], off
	v_or_b32_e32 v6, s19, v45
	v_lshlrev_b32_e32 v36, 11, v6
	v_cvt_pk_bf16_f32 v2, v9, v7
	v_cvt_pk_bf16_f32 v3, v11, v13
	v_cvt_pk_bf16_f32 v4, v15, v17
	v_cvt_pk_bf16_f32 v5, v19, v21
	ds_read2_b32 v[8:9], v53 offset0:16 offset1:24
	ds_read2_b32 v[10:11], v53 offset0:49 offset1:57
	ds_read2_b32 v[12:13], v53 offset0:82 offset1:90
	ds_read2_b32 v[14:15], v53 offset0:115 offset1:123
	ds_read2_b32 v[16:17], v53 offset0:148 offset1:156
	ds_read2_b32 v[18:19], v53 offset0:181 offset1:189
	ds_read2_b32 v[20:21], v53 offset0:214 offset1:222
	ds_read2_b32 v[24:25], v53 offset0:247 offset1:255
	v_lshl_add_u64 v[6:7], v[22:23], 0, v[36:37]
	global_store_dwordx4 v[6:7], v[2:5], off
	v_or_b32_e32 v6, s19, v47
	v_lshlrev_b32_e32 v36, 11, v6
	v_lshl_add_u64 v[6:7], v[22:23], 0, v[36:37]
	s_waitcnt lgkmcnt(6)
	v_cvt_pk_bf16_f32 v2, v8, v10
	s_waitcnt lgkmcnt(4)
	v_cvt_pk_bf16_f32 v3, v12, v14
	s_waitcnt lgkmcnt(2)
	v_cvt_pk_bf16_f32 v4, v16, v18
	s_waitcnt lgkmcnt(0)
	v_cvt_pk_bf16_f32 v5, v20, v24
	global_store_dwordx4 v[6:7], v[2:5], off
	v_or_b32_e32 v6, s19, v51
	v_lshlrev_b32_e32 v36, 11, v6
	v_lshl_add_u64 v[6:7], v[22:23], 0, v[36:37]
	v_cvt_pk_bf16_f32 v2, v9, v11
	v_cvt_pk_bf16_f32 v3, v13, v15
	v_cvt_pk_bf16_f32 v4, v17, v19
	v_cvt_pk_bf16_f32 v5, v21, v25
	global_store_dwordx4 v[6:7], v[2:5], off
	s_waitcnt lgkmcnt(0)

; #define LAS __attribute__((address_space(3)))
; __device__ __forceinline__ unsigned cvt_pk_bf16(float lo, float hi) { unsigned r; asm("v_cvt_pk_bf16_f32 %0, %1, %2" : "=v"(r) : "v"(lo), "v"(hi)); return r; }
; __device__ __forceinline__ void transpose_item(const float* W, int K, int N, const float* gain, bf16_t* WT, int dst_row0, LAS float* scr, int kb, int n0, int lane) {
;     const int k0 = 64 * kb, n4 = (lane & 7) * 4, kr = lane >> 3;
;     f32x4 v[8]; float g[8];
; #pragma unroll
;     for (int i = 0; i < 8; ++i) { v[i] = *(const f32x4*)(W + (size_t)(k0 + kr + 8 * i) * N + n0 + n4); g[i] = gain ? gain[k0 + kr + 8 * i] : 1.0f; }
; #pragma unroll
;     for (int i = 0; i < 8; ++i) { LAS float* d = scr + (kr + 8 * i) * 33 + n4; d[0] = v[i][0] * g[i]; d[1] = v[i][1] * g[i]; d[2] = v[i][2] * g[i]; d[3] = v[i][3] * g[i]; }
;     asm volatile("s_waitcnt lgkmcnt(0)" ::: "memory");
;     const int c = lane & 7;
; #pragma unroll
;     for (int j = 0; j < 4; ++j) { const int n = (lane >> 3) + 8 * j; const LAS float* s = scr + (8 * c) * 33 + n;
;         u32x4 o; o.x = cvt_pk_bf16(s[0 * 33], s[1 * 33]); o.y = cvt_pk_bf16(s[2 * 33], s[3 * 33]); o.z = cvt_pk_bf16(s[4 * 33], s[5 * 33]); o.w = cvt_pk_bf16(s[6 * 33], s[7 * 33]);
;         *(u32x4*)(WT + (size_t)(dst_row0 + n) * K + k0 + 8 * c) = o; }
;     asm volatile("s_waitcnt lgkmcnt(0)" ::: "memory");
; }
; __device__ __forceinline__ void weight_item(const Params& P, unsigned char* ws, LAS float* scr, int l, int r, int lane) {
;     ...
;         if (r < I_DN) { const int kb = r / 32, n0 = (r % 32) * 32; transpose_item(P.in[30] + oU, DFF, D, nullptr, WDb, n0, scr, kb, n0, lane); return; }
.LBB0_117:
	s_andn2_b64 vcc, exec, s[2:3]
	s_cbranch_vccnz .LBB0_119
	s_load_dwordx16 s[64:79], s[0:1], 0xc0
	s_and_b32 s2, s44, 0x3e0
	s_lshl_b64 s[22:23], s[20:21], 2
	s_mul_i32 s16, s18, 0xffffa000
	v_mov_b32_e32 v43, v37
	s_waitcnt lgkmcnt(0)
	s_add_u32 s3, s76, s22
	s_addc_u32 s19, s77, s23
	s_add_i32 s16, s42, s16
	s_and_b32 s16, s16, 0x7fc0
	s_addk_i32 s16, 0xc900
	s_lshl_b32 s22, s2, 2
	v_or_b32_e32 v36, s16, v1
	s_add_u32 s22, s3, s22
	s_addc_u32 s23, s19, 0
	v_or_b32_e32 v4, 8, v36
	v_mov_b32_e32 v5, v37
	v_or_b32_e32 v10, 16, v36
	v_mov_b32_e32 v11, v37
	v_or_b32_e32 v12, 24, v36
	v_mov_b32_e32 v13, v37
	v_or_b32_e32 v18, 32, v36
	v_mov_b32_e32 v19, v37
	v_or_b32_e32 v20, 40, v36
	v_mov_b32_e32 v21, v37
	v_lshl_add_u64 v[30:31], s[22:23], 0, v[42:43]
	v_lshlrev_b64 v[2:3], 12, v[36:37]
	v_lshlrev_b64 v[4:5], 12, v[4:5]
	v_lshlrev_b64 v[10:11], 12, v[10:11]
	v_lshlrev_b64 v[12:13], 12, v[12:13]
	v_lshlrev_b64 v[18:19], 12, v[18:19]
	v_lshlrev_b64 v[20:21], 12, v[20:21]
	v_lshl_add_u64 v[2:3], v[30:31], 0, v[2:3]
	v_lshl_add_u64 v[6:7], v[30:31], 0, v[4:5]
	v_lshl_add_u64 v[10:11], v[30:31], 0, v[10:11]
	v_lshl_add_u64 v[14:15], v[30:31], 0, v[12:13]
	v_lshl_add_u64 v[18:19], v[30:31], 0, v[18:19]
	v_lshl_add_u64 v[22:23], v[30:31], 0, v[20:21]
	global_load_dwordx4 v[2:5], v[2:3], off nt
	s_nop 0
	global_load_dwordx4 v[6:9], v[6:7], off nt
	s_nop 0
	global_load_dwordx4 v[10:13], v[10:11], off nt
	s_nop 0
	global_load_dwordx4 v[14:17], v[14:15], off nt
	s_nop 0
	global_load_dwordx4 v[18:21], v[18:19], off nt
	s_nop 0
	global_load_dwordx4 v[22:25], v[22:23], off nt
	v_or_b32_e32 v26, 48, v36
	v_mov_b32_e32 v27, v37
	v_lshlrev_b64 v[26:27], 12, v[26:27]
	v_lshl_add_u64 v[26:27], v[30:31], 0, v[26:27]
	v_or_b32_e32 v36, 56, v36
	global_load_dwordx4 v[26:29], v[26:27], off nt
	v_lshlrev_b64 v[32:33], 12, v[36:37]
	v_lshl_add_u64 v[30:31], v[30:31], 0, v[32:33]
	global_load_dwordx4 v[30:33], v[30:31], off nt
	v_add_u32_e32 v43, v35, v39
	v_add_u32_e32 v44, 0x420, v43
	v_add_u32_e32 v46, 0x428, v43
	v_add_u32_e32 v50, 0x840, v43
	v_add_u32_e32 v52, 0x848, v43
	v_add_u32_e32 v54, 0xc60, v43
	v_add_u32_e32 v56, 0xc68, v43
	v_add_u32_e32 v58, 0x1080, v43
	v_add_u32_e32 v65, 0x1088, v43
	v_add_u32_e32 v66, 0x14a0, v43
	v_add_u32_e32 v67, 0x14a8, v43
	v_add_u32_e32 v68, 0x18c0, v43
	v_add_u32_e32 v69, 0x18c8, v43
	v_add_u32_e32 v70, 0x1ce0, v43
	v_add_u32_e32 v71, 0x1ce8, v43
	s_lshl_b64 s[22:23], s[16:17], 1
	s_add_u32 s22, s55, s22
	v_lshlrev_b32_e32 v36, 1, v38
	s_addc_u32 s23, s54, s23
	v_lshl_add_u64 v[48:49], s[22:23], 0, v[36:37]
	s_mov_b64 s[22:23], 0x580000
	s_waitcnt vmcnt(7)
	ds_write2_b32 v43, v2, v3 offset1:1
	ds_write2_b32 v43, v4, v5 offset0:2 offset1:3
	s_waitcnt vmcnt(6)
	ds_write2_b32 v44, v6, v7 offset1:1
	ds_write2_b32 v46, v8, v9 offset1:1
	s_waitcnt vmcnt(5)
	ds_write2_b32 v50, v10, v11 offset1:1
	ds_write2_b32 v52, v12, v13 offset1:1
	s_waitcnt vmcnt(4)
	ds_write2_b32 v54, v14, v15 offset1:1
	ds_write2_b32 v56, v16, v17 offset1:1
	s_waitcnt vmcnt(3)
	ds_write2_b32 v58, v18, v19 offset1:1
	ds_write2_b32 v65, v20, v21 offset1:1
	s_waitcnt vmcnt(2)
	ds_write2_b32 v66, v22, v23 offset1:1
	ds_write2_b32 v67, v24, v25 offset1:1
	s_waitcnt vmcnt(1)
	ds_write2_b32 v68, v26, v27 offset1:1
	ds_write2_b32 v69, v28, v29 offset1:1
	s_waitcnt vmcnt(0)
	ds_write2_b32 v70, v30, v31 offset1:1
	ds_write2_b32 v71, v32, v33 offset1:1
	s_waitcnt lgkmcnt(0)
	ds_read2_b32 v[6:7], v53 offset0:33 offset1:41
	ds_read2_b32 v[8:9], v53 offset1:8
	ds_read2_b32 v[10:11], v53 offset0:66 offset1:74
	ds_read2_b32 v[12:13], v53 offset0:99 offset1:107
	ds_read2_b32 v[14:15], v53 offset0:132 offset1:140
	ds_read2_b32 v[16:17], v53 offset0:165 offset1:173
	ds_read2_b32 v[18:19], v53 offset0:198 offset1:206
	ds_read2_b32 v[20:21], v53 offset0:231 offset1:239
	s_waitcnt lgkmcnt(6)
	v_cvt_pk_bf16_f32 v2, v8, v6
	v_or_b32_e32 v6, s2, v1
	v_mul_u32_u24_e32 v6, 0xb00, v6
	v_lshl_add_u64 v[22:23], v[48:49], 0, s[22:23]
	v_lshlrev_b32_e32 v36, 1, v6
	v_or_b32_e32 v6, s2, v45
	v_lshl_add_u64 v[24:25], v[22:23], 0, v[36:37]
	v_mul_u32_u24_e32 v6, 0xb00, v6
	s_waitcnt lgkmcnt(4)
	v_cvt_pk_bf16_f32 v3, v10, v12
	s_waitcnt lgkmcnt(2)
	v_cvt_pk_bf16_f32 v4, v14, v16
	s_waitcnt lgkmcnt(0)
	v_cvt_pk_bf16_f32 v5, v18, v20
	global_store_dwordx4 v[24:25], v[2:5], off
	v_lshlrev_b32_e32 v36, 1, v6
	s_nop 0
	v_cvt_pk_bf16_f32 v2, v9, v7
	v_cvt_pk_bf16_f32 v3, v11, v13
	v_cvt_pk_bf16_f32 v4, v15, v17
	v_cvt_pk_bf16_f32 v5, v19, v21
	v_lshl_add_u64 v[6:7], v[22:23], 0, v[36:37]
	ds_read2_b32 v[8:9], v53 offset0:16 offset1:24
	ds_read2_b32 v[10:11], v53 offset0:49 offset1:57
	ds_read2_b32 v[12:13], v53 offset0:82 offset1:90
	ds_read2_b32 v[14:15], v53 offset0:115 offset1:123
	ds_read2_b32 v[16:17], v53 offset0:148 offset1:156
	ds_read2_b32 v[18:19], v53 offset0:181 offset1:189
	ds_read2_b32 v[20:21], v53 offset0:214 offset1:222
	ds_read2_b32 v[24:25], v53 offset0:247 offset1:255
	global_store_dwordx4 v[6:7], v[2:5], off
	v_or_b32_e32 v6, s2, v47
	v_mul_u32_u24_e32 v6, 0xb00, v6
	v_lshlrev_b32_e32 v36, 1, v6
	v_lshl_add_u64 v[6:7], v[22:23], 0, v[36:37]
	s_waitcnt lgkmcnt(6)
	v_cvt_pk_bf16_f32 v2, v8, v10
	s_waitcnt lgkmcnt(4)
	v_cvt_pk_bf16_f32 v3, v12, v14
	s_waitcnt lgkmcnt(2)
	v_cvt_pk_bf16_f32 v4, v16, v18
	s_waitcnt lgkmcnt(0)
	v_cvt_pk_bf16_f32 v5, v20, v24
	global_store_dwordx4 v[6:7], v[2:5], off
	v_or_b32_e32 v6, s2, v51
	v_mul_u32_u24_e32 v6, 0xb00, v6
	v_lshlrev_b32_e32 v36, 1, v6
	v_lshl_add_u64 v[6:7], v[22:23], 0, v[36:37]
	v_cvt_pk_bf16_f32 v2, v9, v11
	v_cvt_pk_bf16_f32 v3, v13, v15
	v_cvt_pk_bf16_f32 v4, v17, v19
	v_cvt_pk_bf16_f32 v5, v21, v25
	global_store_dwordx4 v[6:7], v[2:5], off
	s_waitcnt lgkmcnt(0)

; #define LAS __attribute__((address_space(3)))
; __device__ __forceinline__ unsigned cvt_pk_bf16(float lo, float hi) { unsigned r; asm("v_cvt_pk_bf16_f32 %0, %1, %2" : "=v"(r) : "v"(lo), "v"(hi)); return r; }
; __device__ __forceinline__ void transpose_item(const float* W, int K, int N, const float* gain, bf16_t* WT, int dst_row0, LAS float* scr, int kb, int n0, int lane) {
;     const int k0 = 64 * kb, n4 = (lane & 7) * 4, kr = lane >> 3;
;     f32x4 v[8]; float g[8];
; #pragma unroll
;     for (int i = 0; i < 8; ++i) { v[i] = *(const f32x4*)(W + (size_t)(k0 + kr + 8 * i) * N + n0 + n4); g[i] = gain ? gain[k0 + kr + 8 * i] : 1.0f; }
; #pragma unroll
;     for (int i = 0; i < 8; ++i) { LAS float* d = scr + (kr + 8 * i) * 33 + n4; d[0] = v[i][0] * g[i]; d[1] = v[i][1] * g[i]; d[2] = v[i][2] * g[i]; d[3] = v[i][3] * g[i]; }
;     asm volatile("s_waitcnt lgkmcnt(0)" ::: "memory");
;     const int c = lane & 7;
; #pragma unroll
;     for (int j = 0; j < 4; ++j) { const int n = (lane >> 3) + 8 * j; const LAS float* s = scr + (8 * c) * 33 + n;
;         u32x4 o; o.x = cvt_pk_bf16(s[0 * 33], s[1 * 33]); o.y = cvt_pk_bf16(s[2 * 33], s[3 * 33]); o.z = cvt_pk_bf16(s[4 * 33], s[5 * 33]); o.w = cvt_pk_bf16(s[6 * 33], s[7 * 33]);
;         *(u32x4*)(WT + (size_t)(dst_row0 + n) * K + k0 + 8 * c) = o; }
;     asm volatile("s_waitcnt lgkmcnt(0)" ::: "memory");
; }
; __device__ __forceinline__ void weight_item(const Params& P, unsigned char* ws, LAS float* scr, int l, int r, int lane) {
;     ...
;         if (r < I_DN) { const int kb = r / 32, n0 = (r % 32) * 32; transpose_item(P.in[12] + oU, DFF, D, nullptr, WDa, n0, scr, kb, n0, lane); return; }
.LBB0_120:
	s_andn2_b64 vcc, exec, s[2:3]
	s_cbranch_vccnz .LBB0_122
	s_load_dwordx16 s[64:79], s[0:1], 0x40
	s_and_b32 s2, s44, 0x3e0
	s_lshl_b64 s[22:23], s[20:21], 2
	v_mov_b32_e32 v43, v37
	v_mov_b32_e32 v5, v37
	s_waitcnt lgkmcnt(0)
	s_add_u32 s3, s72, s22
	s_addc_u32 s19, s73, s23
	s_lshl_b32 s16, s18, 13
	s_sub_i32 s16, s42, s16
	s_and_b32 s16, s16, 0x3fc0
	s_addk_i32 s16, 0xd400
	s_lshl_b32 s22, s2, 2
	v_or_b32_e32 v36, s16, v1
	s_add_u32 s22, s3, s22
	s_addc_u32 s23, s19, 0
	v_or_b32_e32 v4, 8, v36
	v_or_b32_e32 v10, 16, v36
	v_mov_b32_e32 v11, v37
	v_or_b32_e32 v12, 24, v36
	v_mov_b32_e32 v13, v37
	v_or_b32_e32 v18, 32, v36
	v_mov_b32_e32 v19, v37
	v_or_b32_e32 v20, 40, v36
	v_mov_b32_e32 v21, v37
	v_lshl_add_u64 v[30:31], s[22:23], 0, v[42:43]
	v_lshlrev_b64 v[2:3], 12, v[36:37]
	v_lshlrev_b64 v[4:5], 12, v[4:5]
	v_lshlrev_b64 v[10:11], 12, v[10:11]
	v_lshlrev_b64 v[12:13], 12, v[12:13]
	v_lshlrev_b64 v[18:19], 12, v[18:19]
	v_lshlrev_b64 v[20:21], 12, v[20:21]
	v_lshl_add_u64 v[2:3], v[30:31], 0, v[2:3]
	v_lshl_add_u64 v[6:7], v[30:31], 0, v[4:5]
	v_lshl_add_u64 v[10:11], v[30:31], 0, v[10:11]
	v_lshl_add_u64 v[14:15], v[30:31], 0, v[12:13]
	v_lshl_add_u64 v[18:19], v[30:31], 0, v[18:19]
	v_lshl_add_u64 v[22:23], v[30:31], 0, v[20:21]
	global_load_dwordx4 v[2:5], v[2:3], off nt
	s_nop 0
	global_load_dwordx4 v[6:9], v[6:7], off nt
	s_nop 0
	global_load_dwordx4 v[10:13], v[10:11], off nt
	s_nop 0
	global_load_dwordx4 v[14:17], v[14:15], off nt
	s_nop 0
	global_load_dwordx4 v[18:21], v[18:19], off nt
	s_nop 0
	global_load_dwordx4 v[22:25], v[22:23], off nt
	v_or_b32_e32 v26, 48, v36
	v_mov_b32_e32 v27, v37
	v_lshlrev_b64 v[26:27], 12, v[26:27]
	v_lshl_add_u64 v[26:27], v[30:31], 0, v[26:27]
	v_or_b32_e32 v36, 56, v36
	global_load_dwordx4 v[26:29], v[26:27], off nt
	v_lshlrev_b64 v[32:33], 12, v[36:37]
	v_lshl_add_u64 v[30:31], v[30:31], 0, v[32:33]
	global_load_dwordx4 v[30:33], v[30:31], off nt
	v_add_u32_e32 v43, v35, v39
	v_add_u32_e32 v44, 0x420, v43
	v_add_u32_e32 v46, 0x428, v43
	v_add_u32_e32 v48, 0x840, v43
	v_add_u32_e32 v49, 0x848, v43
	v_add_u32_e32 v50, 0xc60, v43
	v_add_u32_e32 v52, 0xc68, v43
	v_add_u32_e32 v54, 0x1080, v43
	v_add_u32_e32 v56, 0x1088, v43
	v_add_u32_e32 v58, 0x14a0, v43
	v_add_u32_e32 v65, 0x14a8, v43
	v_add_u32_e32 v66, 0x18c0, v43
	v_add_u32_e32 v67, 0x18c8, v43
	v_add_u32_e32 v68, 0x1ce0, v43
	v_add_u32_e32 v69, 0x1ce8, v43
	s_lshl_b64 s[22:23], s[16:17], 1
	s_add_u32 s22, s55, s22
	v_lshlrev_b32_e32 v36, 1, v38
	s_addc_u32 s23, s54, s23
	s_waitcnt vmcnt(7)
	ds_write2_b32 v43, v2, v3 offset1:1
	ds_write2_b32 v43, v4, v5 offset0:2 offset1:3
	s_waitcnt vmcnt(6)
	ds_write2_b32 v44, v6, v7 offset1:1
	ds_write2_b32 v46, v8, v9 offset1:1
	s_waitcnt vmcnt(5)
	ds_write2_b32 v48, v10, v11 offset1:1
	ds_write2_b32 v49, v12, v13 offset1:1
	s_waitcnt vmcnt(4)
	ds_write2_b32 v50, v14, v15 offset1:1
	ds_write2_b32 v52, v16, v17 offset1:1
	s_waitcnt vmcnt(3)
	ds_write2_b32 v54, v18, v19 offset1:1
	ds_write2_b32 v56, v20, v21 offset1:1
	s_waitcnt vmcnt(2)
	ds_write2_b32 v58, v22, v23 offset1:1
	ds_write2_b32 v65, v24, v25 offset1:1
	s_waitcnt vmcnt(1)
	ds_write2_b32 v66, v26, v27 offset1:1
	ds_write2_b32 v67, v28, v29 offset1:1
	s_waitcnt vmcnt(0)
	ds_write2_b32 v68, v30, v31 offset1:1
	ds_write2_b32 v69, v32, v33 offset1:1
	s_waitcnt lgkmcnt(0)
	ds_read2_b32 v[6:7], v53 offset0:33 offset1:41
	ds_read2_b32 v[8:9], v53 offset1:8
	ds_read2_b32 v[10:11], v53 offset0:66 offset1:74
	ds_read2_b32 v[12:13], v53 offset0:99 offset1:107
	ds_read2_b32 v[14:15], v53 offset0:132 offset1:140
	ds_read2_b32 v[16:17], v53 offset0:165 offset1:173
	ds_read2_b32 v[18:19], v53 offset0:198 offset1:206
	ds_read2_b32 v[20:21], v53 offset0:231 offset1:239
	s_waitcnt lgkmcnt(6)
	v_cvt_pk_bf16_f32 v2, v8, v6
	v_or_b32_e32 v6, s2, v1
	v_mul_u32_u24_e32 v6, 0xb00, v6
	v_lshl_add_u64 v[22:23], s[22:23], 0, v[36:37]
	v_lshlrev_b32_e32 v36, 1, v6
	v_or_b32_e32 v6, s2, v45
	v_lshl_add_u64 v[24:25], v[22:23], 0, v[36:37]
	v_mul_u32_u24_e32 v6, 0xb00, v6
	s_waitcnt lgkmcnt(4)
	v_cvt_pk_bf16_f32 v3, v10, v12
	s_waitcnt lgkmcnt(2)
	v_cvt_pk_bf16_f32 v4, v14, v16
	s_waitcnt lgkmcnt(0)
	v_cvt_pk_bf16_f32 v5, v18, v20
	global_store_dwordx4 v[24:25], v[2:5], off
	v_lshlrev_b32_e32 v36, 1, v6
	s_nop 0
	v_cvt_pk_bf16_f32 v2, v9, v7
	v_cvt_pk_bf16_f32 v3, v11, v13
	v_cvt_pk_bf16_f32 v4, v15, v17
	v_cvt_pk_bf16_f32 v5, v19, v21
	v_lshl_add_u64 v[6:7], v[22:23], 0, v[36:37]
	ds_read2_b32 v[8:9], v53 offset0:16 offset1:24
	ds_read2_b32 v[10:11], v53 offset0:49 offset1:57
	ds_read2_b32 v[12:13], v53 offset0:82 offset1:90
	ds_read2_b32 v[14:15], v53 offset0:115 offset1:123
	ds_read2_b32 v[16:17], v53 offset0:148 offset1:156
	ds_read2_b32 v[18:19], v53 offset0:181 offset1:189
	ds_read2_b32 v[20:21], v53 offset0:214 offset1:222
	ds_read2_b32 v[24:25], v53 offset0:247 offset1:255
	global_store_dwordx4 v[6:7], v[2:5], off
	v_or_b32_e32 v6, s2, v47
	v_mul_u32_u24_e32 v6, 0xb00, v6
	v_lshlrev_b32_e32 v36, 1, v6
	v_lshl_add_u64 v[6:7], v[22:23], 0, v[36:37]
	s_waitcnt lgkmcnt(6)
	v_cvt_pk_bf16_f32 v2, v8, v10
	s_waitcnt lgkmcnt(4)
	v_cvt_pk_bf16_f32 v3, v12, v14
	s_waitcnt lgkmcnt(2)
	v_cvt_pk_bf16_f32 v4, v16, v18
	s_waitcnt lgkmcnt(0)
	v_cvt_pk_bf16_f32 v5, v20, v24
	global_store_dwordx4 v[6:7], v[2:5], off
	v_or_b32_e32 v6, s2, v51
	v_mul_u32_u24_e32 v6, 0xb00, v6
	v_lshlrev_b32_e32 v36, 1, v6
	v_lshl_add_u64 v[6:7], v[22:23], 0, v[36:37]
	v_cvt_pk_bf16_f32 v2, v9, v11
	v_cvt_pk_bf16_f32 v3, v13, v15
	v_cvt_pk_bf16_f32 v4, v17, v19
	v_cvt_pk_bf16_f32 v5, v21, v25
	global_store_dwordx4 v[6:7], v[2:5], off
	s_waitcnt lgkmcnt(0)
